# attention steps: QK MFMAs accumulator-major with scaling/row-max VALU in the same order (MFMA->VALU distance filled, s_nop padding removed); band K-fragment waits counted
# speedup vs baseline: 1.0087x; 1.0039x over previous
; #define LAS __attribute__((address_space(3)))
; #define MFMA(a, b, c) __builtin_amdgcn_mfma_f32_32x32x16_bf16((a), (b), (c), 0, 0, 0)
; template <int DVT>
; DI void attn_step(lptr sKw, int kpitch, lptr sV, int vpitch, const bf16x8 (&qf)[4], float& m, float& l, f32x16 (&O)[DVT],
;                   const LAS float* tb, bool far, float cfar, int lane) {
;     ...
;     bf16x8 kf[8];
; #pragma unroll
;     for (int s = 0; s < 4; ++s) {
;         kf[2 * s] = *(const LAS bf16x8*)(sKw + r * kpitch + (16 * s + 8 * h) * 2);
;         kf[2 * s + 1] = *(const LAS bf16x8*)(sKw + (32 + r) * kpitch + (16 * s + 8 * h) * 2);
;     }
;     __builtin_amdgcn_sched_barrier(0);
; #pragma unroll
;     for (int s = 0; s < 4; ++s) { p0 = MFMA(kf[2 * s], qf[s], p0); p1 = MFMA(kf[2 * s + 1], qf[s], p1); }
;     const int i16 = lane & 15, q = i16 >> 2, pp = i16 & 3, blk = (lane >> 4) & 1;
;     lptr vb = sV + (4 * h + q) * vpitch + (16 * blk + 4 * pp) * 2;
;     ...
;     ATTN_TAIL(DVT, VADDR_PAD)
.Lb3_noovr:
	s_add_i32 s0, s64, 63
	s_add_i32 s65, s65, 1
	v_cmp_le_u32_e32 vcc, s64, v126
	v_cmp_ge_u32_e64 s[0:1], s0, v128
	s_and_b32 s70, s65, 1
	s_and_b32 s70, s70, s101
	s_and_b64 s[72:73], vcc, s[0:1]
	s_waitcnt lgkmcnt(0)
	s_barrier
	s_and_saveexec_b64 s[0:1], s[72:73]
	s_cbranch_execz .LBB0_220
	s_mul_i32 s71, s70, 0x4800
	v_add_u32_e32 v98, s71, v125
	v_add3_u32 v38, v98, v127, v112
	v_add3_u32 v39, v98, v129, v112
	ds_read_b128 v[34:37], v38
	ds_read_b128 v[50:53], v38 offset:32
	ds_read_b128 v[54:57], v39
	ds_read_b128 v[136:139], v39 offset:32
	ds_read_b128 v[58:61], v38 offset:64
	ds_read_b128 v[62:65], v38 offset:96
	ds_read_b128 v[140:143], v39 offset:64
	ds_read_b128 v[144:147], v39 offset:96
	s_waitcnt lgkmcnt(7)
	v_mfma_f32_32x32x16_bf16 v[34:49], v[34:37], v[66:69], 0
	s_waitcnt lgkmcnt(6)
	v_mfma_f32_32x32x16_bf16 v[34:49], v[50:53], v[70:73], v[34:49]
	v_add_u32_e32 v50, v98, v131
	v_add_u32_e32 v135, v50, v132
	ds_read_b64_tr_b16 v[102:103], v135 offset:9216
	ds_read_b64_tr_b16 v[104:105], v135 offset:10368
	ds_read_b64_tr_b16 v[100:101], v135 offset:10432
	ds_read_b64_tr_b16 v[98:99], v135 offset:9280
	s_waitcnt lgkmcnt(7)
	v_mfma_f32_32x32x16_bf16 v[34:49], v[58:61], v[74:77], v[34:49]
	s_waitcnt lgkmcnt(6)
	v_mfma_f32_32x32x16_bf16 v[34:49], v[62:65], v[78:81], v[34:49]
	v_mfma_f32_32x32x16_bf16 v[50:65], v[54:57], v[66:69], 0
	v_mfma_f32_32x32x16_bf16 v[50:65], v[136:139], v[70:73], v[50:65]
	ds_read2_b32 v[136:137], v134 offset0:58 offset1:59
	ds_read2_b32 v[138:139], v134 offset0:56 offset1:57
	ds_read2_b32 v[148:149], v134 offset0:50 offset1:51
	ds_read2_b32 v[150:151], v134 offset0:48 offset1:49
	ds_read2_b32 v[152:153], v134 offset0:26 offset1:27
	ds_read2_b32 v[154:155], v134 offset0:24 offset1:25
	ds_read2_b32 v[156:157], v134 offset0:18 offset1:19
	ds_read2_b32 v[158:159], v134 offset0:16 offset1:17
	s_waitcnt lgkmcnt(13)
	v_mfma_f32_32x32x16_bf16 v[50:65], v[140:143], v[74:77], v[50:65]
	ds_read2_b32 v[140:141], v134 offset0:42 offset1:43
	ds_read2_b32 v[142:143], v134 offset0:40 offset1:41
	ds_read2_b32 v[160:161], v134 offset0:34 offset1:35
	ds_read2_b32 v[162:163], v134 offset0:32 offset1:33
	ds_read2_b32 v[164:165], v134 offset0:10 offset1:11
	ds_read2_b32 v[166:167], v134 offset0:8 offset1:9
	ds_read2_b32 v[168:169], v134 offset0:2 offset1:3
	ds_read2_b32 v[170:171], v134 offset1:1
	s_waitcnt lgkmcnt(15)
	v_mfma_f32_32x32x16_bf16 v[50:65], v[144:147], v[78:81], v[50:65]
	s_waitcnt lgkmcnt(0)
	v_fmamk_f32 v137, v34, 0x3e38aa3b, v137
	v_fmamk_f32 v35, v35, 0x3e38aa3b, v136
	v_fmamk_f32 v36, v36, 0x3e38aa3b, v139
	v_fmamk_f32 v37, v37, 0x3e38aa3b, v138
	v_fmamk_f32 v38, v38, 0x3e38aa3b, v149
	v_fmamk_f32 v39, v39, 0x3e38aa3b, v148
	v_fmamk_f32 v40, v40, 0x3e38aa3b, v151
	v_fmamk_f32 v41, v41, 0x3e38aa3b, v150
	v_fmamk_f32 v42, v42, 0x3e38aa3b, v141
	v_fmamk_f32 v43, v43, 0x3e38aa3b, v140
	v_fmamk_f32 v44, v44, 0x3e38aa3b, v143
	v_fmamk_f32 v45, v45, 0x3e38aa3b, v142
	v_fmamk_f32 v46, v46, 0x3e38aa3b, v161
	v_fmamk_f32 v47, v47, 0x3e38aa3b, v160
	v_fmamk_f32 v48, v48, 0x3e38aa3b, v163
	v_fmamk_f32 v49, v49, 0x3e38aa3b, v162
	v_max3_f32 v34, v137, v35, v36
	v_max3_f32 v136, v37, v38, v39
	v_max3_f32 v34, v34, v40, v41
	v_max3_f32 v136, v136, v42, v43
	v_max3_f32 v34, v34, v44, v45
	v_max3_f32 v136, v136, v46, v47
	v_max3_f32 v34, v34, v48, v49
	v_fmamk_f32 v50, v50, 0x3e38aa3b, v153
	v_fmamk_f32 v51, v51, 0x3e38aa3b, v152
	v_fmamk_f32 v52, v52, 0x3e38aa3b, v155
	v_fmamk_f32 v53, v53, 0x3e38aa3b, v154
	v_fmamk_f32 v54, v54, 0x3e38aa3b, v157
	v_fmamk_f32 v55, v55, 0x3e38aa3b, v156
	v_fmamk_f32 v56, v56, 0x3e38aa3b, v159
	v_fmamk_f32 v57, v57, 0x3e38aa3b, v158
	v_fmamk_f32 v58, v58, 0x3e38aa3b, v165
	v_fmamk_f32 v59, v59, 0x3e38aa3b, v164
	v_fmamk_f32 v60, v60, 0x3e38aa3b, v167
	v_fmamk_f32 v61, v61, 0x3e38aa3b, v166
	v_fmamk_f32 v62, v62, 0x3e38aa3b, v169
	v_fmamk_f32 v63, v63, 0x3e38aa3b, v168
	v_fmamk_f32 v64, v64, 0x3e38aa3b, v171
	v_fmamk_f32 v65, v65, 0x3e38aa3b, v170
	v_max3_f32 v34, v34, v50, v51
	v_max3_f32 v136, v136, v52, v53
	v_max3_f32 v34, v34, v54, v55
	v_max3_f32 v136, v136, v56, v57
	v_max3_f32 v34, v34, v58, v59
	v_max3_f32 v136, v136, v60, v61
	v_max3_f32 v34, v34, v62, v63
	v_max3_f32 v136, v136, v64, v65
	s_nop 0
	v_max_f32_e32 v136, v136, v136
	v_max_f32_e32 v34, v34, v34
	v_max_f32_e32 v34, v34, v136
	v_mov_b32_e32 v136, v34
	s_nop 1
	v_permlane32_swap_b32_e32 v34, v136
	v_max_f32_e32 v136, v136, v136
	v_max_f32_e32 v34, v34, v34
	v_max_f32_e32 v34, v34, v136
	v_sub_f32_e32 v136, v34, v133
	v_cmp_lt_f32_e32 vcc, s45, v136
	v_max_f32_e32 v34, v133, v34
	s_nop 0
	v_cndmask_b32_e32 v34, v133, v34, vcc
	v_sub_f32 v136, v137, v34
	v_sub_f32 v50, v50, v34
	v_sub_f32 v51, v51, v34
	v_sub_f32 v36, v36, v34
	v_sub_f32 v52, v52, v34
	v_sub_f32 v53, v53, v34
	v_sub_f32 v54, v54, v34
	v_sub_f32 v39, v39, v34
	v_sub_f32 v55, v55, v34
	v_sub_f32 v40, v40, v34
	v_sub_f32 v56, v56, v34
	v_sub_f32 v57, v57, v34
	v_sub_f32 v58, v58, v34
	v_sub_f32 v43, v43, v34
	v_sub_f32 v44, v44, v34
	v_sub_f32 v47, v47, v34
	v_sub_f32 v48, v48, v34
	v_sub_f32 v137, v35, v34
	v_sub_f32 v138, v37, v34
	v_sub_f32 v139, v38, v34
	v_sub_f32 v140, v41, v34
	v_sub_f32 v141, v42, v34
	v_sub_f32 v142, v59, v34
	v_sub_f32 v143, v60, v34
	v_sub_f32 v144, v45, v34
	v_sub_f32 v145, v61, v34
	v_sub_f32 v146, v46, v34
	v_sub_f32 v147, v62, v34
	v_sub_f32 v148, v63, v34
	v_sub_f32 v149, v64, v34
	v_sub_f32 v150, v49, v34
	v_sub_f32 v151, v65, v34
	s_nop 0
	v_exp_f32_e32 v59, v136
	v_exp_f32_e32 v35, v50
	v_exp_f32_e32 v60, v137
	v_exp_f32_e32 v37, v51
	v_exp_f32_e32 v61, v36
	v_exp_f32_e32 v38, v52
	v_exp_f32_e32 v62, v138
	v_exp_f32_e32 v41, v53
	v_exp_f32_e32 v63, v139
	v_exp_f32_e32 v42, v54
	v_exp_f32_e32 v64, v39
	v_exp_f32_e32 v45, v55
	v_exp_f32_e32 v65, v40
	v_exp_f32_e32 v46, v56
	v_exp_f32_e32 v136, v140
	v_exp_f32_e32 v49, v57
	v_exp_f32_e32 v51, v141
	v_exp_f32_e32 v36, v58
	v_exp_f32_e32 v52, v43
	v_exp_f32_e32 v39, v142
	v_exp_f32_e32 v53, v44
	v_exp_f32_e32 v40, v143
	v_exp_f32_e32 v54, v144
	v_exp_f32_e32 v43, v145
	v_exp_f32_e32 v55, v146
	v_exp_f32_e32 v44, v147
	v_exp_f32_e32 v56, v47
	v_exp_f32_e32 v47, v148
	v_exp_f32_e32 v57, v48
	v_exp_f32_e32 v48, v149
	v_exp_f32_e32 v58, v150
	v_exp_f32_e32 v50, v151
	v_add_f32 v137, v59, v35
	v_add_f32 v138, v51, v36
	v_add_f32 v139, v52, v39
	v_add_f32 v140, v53, v40
	v_add_f32 v141, v54, v43
	v_add_f32 v142, v55, v44
	s_nop 1
	s_nop 0
	v_add_f32 v137, v137, v138
	v_add_f32 v138, v60, v37
	v_add_f32 v143, v56, v47
	v_add_f32 v144, v57, v48
	v_cmp_neq_f32_e32 vcc, v34, v133
	v_add_f32 v138, v138, v139
	v_add_f32 v139, v61, v38
	v_add_f32 v145, v58, v50
	s_nop 0
	v_add_f32 v139, v139, v140
	v_add_f32 v140, v62, v41
	v_add_f32 v137, v137, v138
	s_nop 0
	v_add_f32 v140, v140, v141
	v_add_f32 v141, v63, v42
	s_nop 0
	v_add_f32 v141, v141, v142
	v_add_f32 v142, v64, v45
	v_add_f32 v138, v139, v140
	s_nop 0
	v_add_f32 v142, v142, v143
	v_add_f32 v143, v65, v46
	v_add_f32 v137, v137, v138
	s_nop 0
	v_add_f32 v143, v143, v144
	v_add_f32 v144, v136, v49
	v_add_f32 v138, v141, v142
	s_nop 0
	v_add_f32 v144, v144, v145
	s_nop 0
	v_add_f32 v139, v143, v144
	s_nop 0
	v_add_f32 v138, v138, v139
	s_nop 0
	v_add_f32 v137, v137, v138
	s_cbranch_vccz .LBB0_219
	v_sub_f32_e32 v133, v133, v34
	v_exp_f32_e32 v138, v133
	s_nop 0
	v_mul_f32_e32 v124, v124, v138
	v_pk_mul_f32 v[32:33], v[32:33], v[138:139] op_sel_hi:[1,0]
	v_pk_mul_f32 v[30:31], v[30:31], v[138:139] op_sel_hi:[1,0]
	v_pk_mul_f32 v[28:29], v[28:29], v[138:139] op_sel_hi:[1,0]
	v_pk_mul_f32 v[26:27], v[26:27], v[138:139] op_sel_hi:[1,0]
	v_pk_mul_f32 v[24:25], v[24:25], v[138:139] op_sel_hi:[1,0]
	v_pk_mul_f32 v[22:23], v[22:23], v[138:139] op_sel_hi:[1,0]
	v_pk_mul_f32 v[20:21], v[20:21], v[138:139] op_sel_hi:[1,0]
	v_pk_mul_f32 v[18:19], v[18:19], v[138:139] op_sel_hi:[1,0]
	v_pk_mul_f32 v[16:17], v[16:17], v[138:139] op_sel_hi:[1,0]
	v_pk_mul_f32 v[14:15], v[14:15], v[138:139] op_sel_hi:[1,0]
	v_pk_mul_f32 v[12:13], v[12:13], v[138:139] op_sel_hi:[1,0]
	v_pk_mul_f32 v[10:11], v[10:11], v[138:139] op_sel_hi:[1,0]
	v_pk_mul_f32 v[8:9], v[8:9], v[138:139] op_sel_hi:[1,0]
	v_pk_mul_f32 v[6:7], v[6:7], v[138:139] op_sel_hi:[1,0]
	v_pk_mul_f32 v[4:5], v[4:5], v[138:139] op_sel_hi:[1,0]
	v_pk_mul_f32 v[2:3], v[2:3], v[138:139] op_sel_hi:[1,0]

; #define LAS __attribute__((address_space(3)))
; #define MFMA(a, b, c) __builtin_amdgcn_mfma_f32_32x32x16_bf16((a), (b), (c), 0, 0, 0)
; template <typename F>
; DI void diff_step(lptr sK, lptr sV, int kx0, int vl0, const bf16x8 (&qf)[4], float& m, float& l, f32x16 (&O)[4],
;                   const LAS float* tb, bool far, float cfar, int lane, F&& mid) {
;     ...
;     lptr kr = sK + r * 256;
;     bf16x8 kf[8];
; #pragma unroll
;     for (int s = 0; s < 4; ++s) {
;         const int co = (kx0 ^ (2 * s)) * 16;
;         kf[2 * s] = *(const LAS bf16x8*)(kr + co);
;         kf[2 * s + 1] = *(const LAS bf16x8*)(kr + 8192 + co);
;     }
;     __builtin_amdgcn_sched_barrier(0);
;     mid();
;     __builtin_amdgcn_sched_barrier(0);
; #pragma unroll
;     for (int s = 0; s < 4; ++s) { p0 = MFMA(kf[2 * s], qf[s], p0); p1 = MFMA(kf[2 * s + 1], qf[s], p1); }
;     ...
;     ATTN_TAIL(4, VADDR_SWZ)
.Ldu_A:
	s_waitcnt vmcnt(0)
	s_waitcnt lgkmcnt(0)
	s_barrier
	ds_read_b128 v[80:83], v14
	ds_read_b128 v[120:123], v15
	ds_read_b128 v[116:119], v221
	ds_read_b128 v[10:13], v222
	ds_read_b128 v[84:87], v14 offset:8192
	ds_read_b128 v[6:9], v15 offset:8192
	ds_read_b128 v[2:5], v221 offset:8192
	ds_read_b128 v[112:115], v222 offset:8192
	v_add_u32_e32 v220, 1, v220
	s_add_u32 s72, s63, 0x8000
	s_mov_b32 m0, s72
	s_nop 0
	global_load_lds_dwordx4 v170, s[64:65]
	s_add_u32 s72, s63, 0xc000
	s_mov_b32 m0, s72
	s_nop 0
	global_load_lds_dwordx4 v170, s[70:71]
	s_add_u32 s72, s63, 0x8400
	s_mov_b32 m0, s72
	s_nop 0
	global_load_lds_dwordx4 v172, s[64:65]
	s_add_u32 s72, s63, 0xc400
	s_mov_b32 m0, s72
	s_nop 0
	global_load_lds_dwordx4 v172, s[70:71]
	s_add_u32 s64, s64, 0xe0000
	s_addc_u32 s65, s65, 0
	s_add_u32 s70, s70, 0xe0000
	s_addc_u32 s71, s71, 0
	v_cmp_gt_i32_e32 vcc, s42, v217
	s_waitcnt lgkmcnt(7)
	v_mfma_f32_32x32x16_bf16 v[96:111], v[80:83], v[144:147], 0
	s_waitcnt lgkmcnt(6)
	v_mfma_f32_32x32x16_bf16 v[96:111], v[120:123], v[148:151], v[96:111]
	s_waitcnt lgkmcnt(5)
	v_mfma_f32_32x32x16_bf16 v[96:111], v[116:119], v[152:155], v[96:111]
	s_waitcnt lgkmcnt(4)
	v_mfma_f32_32x32x16_bf16 v[96:111], v[10:13], v[156:159], v[96:111]
	ds_read_b64_tr_b16 v[10:11], v213 offset:16384
	ds_read_b64_tr_b16 v[12:13], v214 offset:18432
	ds_read_b64_tr_b16 v[160:161], v215 offset:16384
	ds_read_b64_tr_b16 v[162:163], v216 offset:18432
	s_waitcnt lgkmcnt(7)
	v_mfma_f32_32x32x16_bf16 v[80:95], v[84:87], v[144:147], 0
	s_waitcnt lgkmcnt(6)
	v_mfma_f32_32x32x16_bf16 v[80:95], v[6:9], v[148:151], v[80:95]
	ds_read_b64_tr_b16 v[6:7], v211 offset:16384
	ds_read_b64_tr_b16 v[8:9], v212 offset:18432
	s_waitcnt lgkmcnt(7)
	v_mfma_f32_32x32x16_bf16 v[80:95], v[2:5], v[152:155], v[80:95]
	ds_read_b64_tr_b16 v[2:3], v199 offset:16384
	ds_read_b64_tr_b16 v[4:5], v210 offset:18432
	s_waitcnt lgkmcnt(8)
	v_mfma_f32_32x32x16_bf16 v[80:95], v[112:115], v[156:159], v[80:95]
	s_and_saveexec_b64 s[22:23], vcc
	s_xor_b64 s[22:23], exec, s[22:23]
	s_cbranch_execz .LBB0_258_a
	ds_read2_b32 v[112:113], v218 offset0:58 offset1:59
	ds_read2_b32 v[114:115], v218 offset0:56 offset1:57
	ds_read2_b32 v[116:117], v218 offset0:50 offset1:51
	ds_read2_b32 v[118:119], v218 offset0:48 offset1:49
	ds_read2_b32 v[128:129], v218 offset0:42 offset1:43
	ds_read2_b32 v[130:131], v218 offset0:40 offset1:41
	ds_read2_b32 v[132:133], v218 offset0:34 offset1:35
	ds_read2_b32 v[134:135], v218 offset0:32 offset1:33
	ds_read2_b32 v[120:121], v218 offset0:26 offset1:27
	ds_read2_b32 v[122:123], v218 offset0:24 offset1:25
	ds_read2_b32 v[124:125], v218 offset0:18 offset1:19
	ds_read2_b32 v[126:127], v218 offset0:16 offset1:17
	ds_read2_b32 v[136:137], v218 offset0:10 offset1:11
	ds_read2_b32 v[138:139], v218 offset0:8 offset1:9
	ds_read2_b32 v[140:141], v218 offset0:2 offset1:3
	ds_read2_b32 v[142:143], v218 offset1:1
	s_waitcnt lgkmcnt(8)
	v_fmamk_f32 v96, v96, 0x3e38aa3b, v113
	v_fmamk_f32 v97, v97, 0x3e38aa3b, v112
	v_fmamk_f32 v98, v98, 0x3e38aa3b, v115
	v_fmamk_f32 v99, v99, 0x3e38aa3b, v114
	v_fmamk_f32 v100, v100, 0x3e38aa3b, v117
	v_fmamk_f32 v101, v101, 0x3e38aa3b, v116
	v_fmamk_f32 v102, v102, 0x3e38aa3b, v119
	v_fmamk_f32 v103, v103, 0x3e38aa3b, v118
	v_fmamk_f32 v104, v104, 0x3e38aa3b, v129
	v_fmamk_f32 v105, v105, 0x3e38aa3b, v128
	v_fmamk_f32 v106, v106, 0x3e38aa3b, v131
	v_fmamk_f32 v107, v107, 0x3e38aa3b, v130
	v_fmamk_f32 v108, v108, 0x3e38aa3b, v133
	v_fmamk_f32 v109, v109, 0x3e38aa3b, v132
	v_fmamk_f32 v110, v110, 0x3e38aa3b, v135
	v_fmamk_f32 v111, v111, 0x3e38aa3b, v134
	v_max3_f32 v112, v96, v97, v98
	v_max3_f32 v113, v99, v100, v101
	v_max3_f32 v112, v112, v102, v103
	v_max3_f32 v113, v113, v104, v105
	v_max3_f32 v112, v112, v106, v107
	v_max3_f32 v113, v113, v108, v109
	v_max3_f32 v112, v112, v110, v111
	s_waitcnt lgkmcnt(0)
	v_fmamk_f32 v80, v80, 0x3e38aa3b, v121
	v_fmamk_f32 v81, v81, 0x3e38aa3b, v120
	v_fmamk_f32 v82, v82, 0x3e38aa3b, v123
	v_fmamk_f32 v83, v83, 0x3e38aa3b, v122
	v_fmamk_f32 v84, v84, 0x3e38aa3b, v125
	v_fmamk_f32 v85, v85, 0x3e38aa3b, v124
	v_fmamk_f32 v86, v86, 0x3e38aa3b, v127
	v_fmamk_f32 v87, v87, 0x3e38aa3b, v126
	v_fmamk_f32 v88, v88, 0x3e38aa3b, v137
	v_fmamk_f32 v89, v89, 0x3e38aa3b, v136
	v_fmamk_f32 v90, v90, 0x3e38aa3b, v139
	v_fmamk_f32 v91, v91, 0x3e38aa3b, v138
	v_fmamk_f32 v92, v92, 0x3e38aa3b, v141
	v_fmamk_f32 v93, v93, 0x3e38aa3b, v140
	v_fmamk_f32 v94, v94, 0x3e38aa3b, v143
	v_fmamk_f32 v95, v95, 0x3e38aa3b, v142
	v_max3_f32 v112, v112, v80, v81
	v_max3_f32 v113, v113, v82, v83
	v_max3_f32 v112, v112, v84, v85
	v_max3_f32 v113, v113, v86, v87
	v_max3_f32 v112, v112, v88, v89
	v_max3_f32 v113, v113, v90, v91
	v_max3_f32 v112, v112, v92, v93
	v_max3_f32 v113, v113, v94, v95
	s_nop 0
	v_max_f32_e32 v113, v113, v113
	v_max_f32_e32 v112, v112, v112
	v_max_f32_e32 v112, v112, v113
	v_mov_b32_e32 v113, v112
	s_nop 1
	v_permlane32_swap_b32_e32 v112, v113
	v_max_f32_e32 v113, v113, v113
	v_max_f32_e32 v112, v112, v112
	v_max_f32_e32 v112, v112, v113
	v_sub_f32_e32 v113, v112, v226
	v_cmp_lt_f32_e32 vcc, s45, v113
	v_max_f32_e32 v112, v226, v112
	s_nop 0
	v_cndmask_b32_e32 v227, v226, v112, vcc
	v_sub_f32 v112, v96, v227
	v_sub_f32 v128, v80, v227
	v_sub_f32 v113, v97, v227
	v_sub_f32 v129, v81, v227
	v_sub_f32 v114, v98, v227
	v_sub_f32 v130, v82, v227
	v_sub_f32 v115, v99, v227
	v_sub_f32 v131, v83, v227
	v_sub_f32 v116, v100, v227
	v_sub_f32 v132, v84, v227
	v_sub_f32 v117, v101, v227
	v_sub_f32 v133, v85, v227
	v_sub_f32 v118, v102, v227
	v_sub_f32 v134, v86, v227
	v_sub_f32 v119, v103, v227
	v_sub_f32 v135, v87, v227
	v_sub_f32 v120, v104, v227
	v_sub_f32 v136, v88, v227
	v_sub_f32 v121, v105, v227
	v_sub_f32 v137, v89, v227
	v_sub_f32 v122, v106, v227
	v_sub_f32 v138, v90, v227
	v_sub_f32 v123, v107, v227
	v_sub_f32 v139, v91, v227
	v_sub_f32 v124, v108, v227
	v_sub_f32 v140, v92, v227
	v_sub_f32 v125, v109, v227
	v_sub_f32 v141, v93, v227
	v_sub_f32 v126, v110, v227
	v_sub_f32 v142, v94, v227
	v_sub_f32 v127, v111, v227
	v_sub_f32 v143, v95, v227
.LBB0_258_a:
	s_andn2_saveexec_b64 s[22:23], s[22:23]
	s_cbranch_execz .LBB0_260_a
	v_sub_f32_e32 v243, v198, v226
	v_fmamk_f32 v112, v96, 0x3e38aa3b, v243
	v_fmamk_f32 v113, v97, 0x3e38aa3b, v243
	v_fmamk_f32 v114, v98, 0x3e38aa3b, v243
	v_fmamk_f32 v115, v99, 0x3e38aa3b, v243
	v_fmamk_f32 v116, v100, 0x3e38aa3b, v243
	v_fmamk_f32 v117, v101, 0x3e38aa3b, v243
	v_fmamk_f32 v118, v102, 0x3e38aa3b, v243
	v_fmamk_f32 v119, v103, 0x3e38aa3b, v243
	v_fmamk_f32 v120, v104, 0x3e38aa3b, v243
	v_fmamk_f32 v121, v105, 0x3e38aa3b, v243
	v_fmamk_f32 v122, v106, 0x3e38aa3b, v243
	v_fmamk_f32 v123, v107, 0x3e38aa3b, v243
	v_fmamk_f32 v124, v108, 0x3e38aa3b, v243
	v_fmamk_f32 v125, v109, 0x3e38aa3b, v243
	v_fmamk_f32 v126, v110, 0x3e38aa3b, v243
	v_fmamk_f32 v127, v111, 0x3e38aa3b, v243
	v_max3_f32 v244, v96, v97, v98
	v_max3_f32 v245, v99, v100, v101
	v_max3_f32 v244, v244, v102, v103
	v_max3_f32 v245, v245, v104, v105
	v_max3_f32 v244, v244, v106, v107
	v_max3_f32 v245, v245, v108, v109
	v_max3_f32 v244, v244, v110, v111
	v_fmamk_f32 v128, v80, 0x3e38aa3b, v243
	v_fmamk_f32 v129, v81, 0x3e38aa3b, v243
	v_fmamk_f32 v130, v82, 0x3e38aa3b, v243
	v_fmamk_f32 v131, v83, 0x3e38aa3b, v243
	v_fmamk_f32 v132, v84, 0x3e38aa3b, v243
	v_fmamk_f32 v133, v85, 0x3e38aa3b, v243
	v_fmamk_f32 v134, v86, 0x3e38aa3b, v243
	v_fmamk_f32 v135, v87, 0x3e38aa3b, v243
	v_fmamk_f32 v136, v88, 0x3e38aa3b, v243
	v_fmamk_f32 v137, v89, 0x3e38aa3b, v243
	v_fmamk_f32 v138, v90, 0x3e38aa3b, v243
	v_fmamk_f32 v139, v91, 0x3e38aa3b, v243
	v_fmamk_f32 v140, v92, 0x3e38aa3b, v243
	v_fmamk_f32 v141, v93, 0x3e38aa3b, v243
	v_fmamk_f32 v142, v94, 0x3e38aa3b, v243
	v_fmamk_f32 v143, v95, 0x3e38aa3b, v243
	v_max3_f32 v244, v244, v80, v81
	v_max3_f32 v245, v245, v82, v83
	v_max3_f32 v244, v244, v84, v85
	v_max3_f32 v245, v245, v86, v87
	v_max3_f32 v244, v244, v88, v89
	v_max3_f32 v245, v245, v90, v91
	v_max3_f32 v244, v244, v92, v93
	v_max3_f32 v245, v245, v94, v95
	v_max_f32_e32 v244, v244, v245
	v_mov_b32_e32 v245, v244
	s_nop 1
	v_permlane32_swap_b32_e32 v244, v245
	v_max_f32_e32 v244, v244, v245
	v_fmamk_f32 v244, v244, 0x3e38aa3b, v198
	v_sub_f32_e32 v245, v244, v226
	v_cmp_lt_f32_e32 vcc, s45, v245
	v_max_f32_e32 v244, v226, v244
	s_nop 0
	v_cndmask_b32_e32 v227, v226, v244, vcc
	s_nop 2
	s_cbranch_vccz .Ldf_far_nofix_a
	v_sub_f32_e32 v243, v198, v227
	v_fmamk_f32 v112, v96, 0x3e38aa3b, v243
	v_fmamk_f32 v128, v80, 0x3e38aa3b, v243
	v_fmamk_f32 v113, v97, 0x3e38aa3b, v243
	v_fmamk_f32 v129, v81, 0x3e38aa3b, v243
	v_fmamk_f32 v114, v98, 0x3e38aa3b, v243
	v_fmamk_f32 v130, v82, 0x3e38aa3b, v243
	v_fmamk_f32 v115, v99, 0x3e38aa3b, v243
	v_fmamk_f32 v131, v83, 0x3e38aa3b, v243
	v_fmamk_f32 v116, v100, 0x3e38aa3b, v243
	v_fmamk_f32 v132, v84, 0x3e38aa3b, v243
	v_fmamk_f32 v117, v101, 0x3e38aa3b, v243
	v_fmamk_f32 v133, v85, 0x3e38aa3b, v243
	v_fmamk_f32 v118, v102, 0x3e38aa3b, v243
	v_fmamk_f32 v134, v86, 0x3e38aa3b, v243
	v_fmamk_f32 v119, v103, 0x3e38aa3b, v243
	v_fmamk_f32 v135, v87, 0x3e38aa3b, v243
	v_fmamk_f32 v120, v104, 0x3e38aa3b, v243
	v_fmamk_f32 v136, v88, 0x3e38aa3b, v243
	v_fmamk_f32 v121, v105, 0x3e38aa3b, v243
	v_fmamk_f32 v137, v89, 0x3e38aa3b, v243
	v_fmamk_f32 v122, v106, 0x3e38aa3b, v243
	v_fmamk_f32 v138, v90, 0x3e38aa3b, v243
	v_fmamk_f32 v123, v107, 0x3e38aa3b, v243
	v_fmamk_f32 v139, v91, 0x3e38aa3b, v243
	v_fmamk_f32 v124, v108, 0x3e38aa3b, v243
	v_fmamk_f32 v140, v92, 0x3e38aa3b, v243
	v_fmamk_f32 v125, v109, 0x3e38aa3b, v243
	v_fmamk_f32 v141, v93, 0x3e38aa3b, v243
	v_fmamk_f32 v126, v110, 0x3e38aa3b, v243
	v_fmamk_f32 v142, v94, 0x3e38aa3b, v243
	v_fmamk_f32 v127, v111, 0x3e38aa3b, v243
	v_fmamk_f32 v143, v95, 0x3e38aa3b, v243

; #define LAS __attribute__((address_space(3)))
; #define MFMA(a, b, c) __builtin_amdgcn_mfma_f32_32x32x16_bf16((a), (b), (c), 0, 0, 0)
; template <typename F>
; DI void diff_step(lptr sK, lptr sV, int kx0, int vl0, const bf16x8 (&qf)[4], float& m, float& l, f32x16 (&O)[4],
;                   const LAS float* tb, bool far, float cfar, int lane, F&& mid) {
;     ...
;     lptr kr = sK + r * 256;
;     bf16x8 kf[8];
; #pragma unroll
;     for (int s = 0; s < 4; ++s) {
;         const int co = (kx0 ^ (2 * s)) * 16;
;         kf[2 * s] = *(const LAS bf16x8*)(kr + co);
;         kf[2 * s + 1] = *(const LAS bf16x8*)(kr + 8192 + co);
;     }
;     __builtin_amdgcn_sched_barrier(0);
;     mid();
;     __builtin_amdgcn_sched_barrier(0);
; #pragma unroll
;     for (int s = 0; s < 4; ++s) { p0 = MFMA(kf[2 * s], qf[s], p0); p1 = MFMA(kf[2 * s + 1], qf[s], p1); }
;     ...
;     ATTN_TAIL(4, VADDR_SWZ)
.Ldu_B:
	s_waitcnt vmcnt(0)
	s_sub_i32 s22, s50, 64
	v_cmp_le_u32_e32 vcc, s22, v200
	v_add_u32_e32 v0, 1, v220
	s_waitcnt lgkmcnt(0)
	s_barrier
	s_and_saveexec_b64 s[22:23], vcc
	s_xor_b64 s[40:41], exec, s[22:23]
	s_cbranch_execz .LBB0_263_b
	v_add_u32_e32 v220, 1, v220
	v_cmp_gt_u32_e32 vcc, s49, v220
	ds_read_b128 v[80:83], v14 offset:32768
	ds_read_b128 v[120:123], v15 offset:32768
	ds_read_b128 v[116:119], v221 offset:32768
	ds_read_b128 v[10:13], v222 offset:32768
	ds_read_b128 v[84:87], v14 offset:40960
	ds_read_b128 v[6:9], v15 offset:40960
	ds_read_b128 v[2:5], v221 offset:40960
	ds_read_b128 v[112:115], v222 offset:40960
	s_and_saveexec_b64 s[22:23], vcc
	s_cbranch_execz .LBB0_256_b
	s_mov_b32 s72, s63
	s_mov_b32 m0, s72
	s_nop 0
	global_load_lds_dwordx4 v170, s[64:65]
	s_add_u32 s72, s63, 0x4000
	s_mov_b32 m0, s72
	s_nop 0
	global_load_lds_dwordx4 v170, s[70:71]
	s_add_u32 s72, s63, 0x400
	s_mov_b32 m0, s72
	s_nop 0
	global_load_lds_dwordx4 v172, s[64:65]
	s_add_u32 s72, s63, 0x4400
	s_mov_b32 m0, s72
	s_nop 0
	global_load_lds_dwordx4 v172, s[70:71]
	s_add_u32 s64, s64, 0xe0000
	s_addc_u32 s65, s65, 0
	s_add_u32 s70, s70, 0xe0000
	s_addc_u32 s71, s71, 0
.LBB0_256_b:
	s_or_b64 exec, exec, s[22:23]
	v_cmp_gt_i32_e32 vcc, s42, v217
	s_waitcnt lgkmcnt(7)
	v_mfma_f32_32x32x16_bf16 v[96:111], v[80:83], v[144:147], 0
	s_waitcnt lgkmcnt(6)
	v_mfma_f32_32x32x16_bf16 v[96:111], v[120:123], v[148:151], v[96:111]
	s_waitcnt lgkmcnt(5)
	v_mfma_f32_32x32x16_bf16 v[96:111], v[116:119], v[152:155], v[96:111]
	s_waitcnt lgkmcnt(4)
	v_mfma_f32_32x32x16_bf16 v[96:111], v[10:13], v[156:159], v[96:111]
	ds_read_b64_tr_b16 v[10:11], v213 offset:49152
	ds_read_b64_tr_b16 v[12:13], v214 offset:51200
	ds_read_b64_tr_b16 v[160:161], v215 offset:49152
	ds_read_b64_tr_b16 v[162:163], v216 offset:51200
	s_waitcnt lgkmcnt(7)
	v_mfma_f32_32x32x16_bf16 v[80:95], v[84:87], v[144:147], 0
	s_waitcnt lgkmcnt(6)
	v_mfma_f32_32x32x16_bf16 v[80:95], v[6:9], v[148:151], v[80:95]
	ds_read_b64_tr_b16 v[6:7], v211 offset:49152
	ds_read_b64_tr_b16 v[8:9], v212 offset:51200
	s_waitcnt lgkmcnt(7)
	v_mfma_f32_32x32x16_bf16 v[80:95], v[2:5], v[152:155], v[80:95]
	ds_read_b64_tr_b16 v[2:3], v199 offset:49152
	ds_read_b64_tr_b16 v[4:5], v210 offset:51200
	s_waitcnt lgkmcnt(8)
	v_mfma_f32_32x32x16_bf16 v[80:95], v[112:115], v[156:159], v[80:95]
	s_and_saveexec_b64 s[22:23], vcc
	s_xor_b64 s[22:23], exec, s[22:23]
	s_cbranch_execz .LBB0_258_b
	ds_read2_b32 v[112:113], v218 offset0:58 offset1:59
	ds_read2_b32 v[114:115], v218 offset0:56 offset1:57
	ds_read2_b32 v[116:117], v218 offset0:50 offset1:51
	ds_read2_b32 v[118:119], v218 offset0:48 offset1:49
	ds_read2_b32 v[128:129], v218 offset0:42 offset1:43
	ds_read2_b32 v[130:131], v218 offset0:40 offset1:41
	ds_read2_b32 v[132:133], v218 offset0:34 offset1:35
	ds_read2_b32 v[134:135], v218 offset0:32 offset1:33
	ds_read2_b32 v[120:121], v218 offset0:26 offset1:27
	ds_read2_b32 v[122:123], v218 offset0:24 offset1:25
	ds_read2_b32 v[124:125], v218 offset0:18 offset1:19
	ds_read2_b32 v[126:127], v218 offset0:16 offset1:17
	ds_read2_b32 v[136:137], v218 offset0:10 offset1:11
	ds_read2_b32 v[138:139], v218 offset0:8 offset1:9
	ds_read2_b32 v[140:141], v218 offset0:2 offset1:3
	ds_read2_b32 v[142:143], v218 offset1:1
	s_waitcnt lgkmcnt(8)
	v_fmamk_f32 v96, v96, 0x3e38aa3b, v113
	v_fmamk_f32 v97, v97, 0x3e38aa3b, v112
	v_fmamk_f32 v98, v98, 0x3e38aa3b, v115
	v_fmamk_f32 v99, v99, 0x3e38aa3b, v114
	v_fmamk_f32 v100, v100, 0x3e38aa3b, v117
	v_fmamk_f32 v101, v101, 0x3e38aa3b, v116
	v_fmamk_f32 v102, v102, 0x3e38aa3b, v119
	v_fmamk_f32 v103, v103, 0x3e38aa3b, v118
	v_fmamk_f32 v104, v104, 0x3e38aa3b, v129
	v_fmamk_f32 v105, v105, 0x3e38aa3b, v128
	v_fmamk_f32 v106, v106, 0x3e38aa3b, v131
	v_fmamk_f32 v107, v107, 0x3e38aa3b, v130
	v_fmamk_f32 v108, v108, 0x3e38aa3b, v133
	v_fmamk_f32 v109, v109, 0x3e38aa3b, v132
	v_fmamk_f32 v110, v110, 0x3e38aa3b, v135
	v_fmamk_f32 v111, v111, 0x3e38aa3b, v134
	v_max3_f32 v112, v96, v97, v98
	v_max3_f32 v113, v99, v100, v101
	v_max3_f32 v112, v112, v102, v103
	v_max3_f32 v113, v113, v104, v105
	v_max3_f32 v112, v112, v106, v107
	v_max3_f32 v113, v113, v108, v109
	v_max3_f32 v112, v112, v110, v111
	s_waitcnt lgkmcnt(0)
	v_fmamk_f32 v80, v80, 0x3e38aa3b, v121
	v_fmamk_f32 v81, v81, 0x3e38aa3b, v120
	v_fmamk_f32 v82, v82, 0x3e38aa3b, v123
	v_fmamk_f32 v83, v83, 0x3e38aa3b, v122
	v_fmamk_f32 v84, v84, 0x3e38aa3b, v125
	v_fmamk_f32 v85, v85, 0x3e38aa3b, v124
	v_fmamk_f32 v86, v86, 0x3e38aa3b, v127
	v_fmamk_f32 v87, v87, 0x3e38aa3b, v126
	v_fmamk_f32 v88, v88, 0x3e38aa3b, v137
	v_fmamk_f32 v89, v89, 0x3e38aa3b, v136
	v_fmamk_f32 v90, v90, 0x3e38aa3b, v139
	v_fmamk_f32 v91, v91, 0x3e38aa3b, v138
	v_fmamk_f32 v92, v92, 0x3e38aa3b, v141
	v_fmamk_f32 v93, v93, 0x3e38aa3b, v140
	v_fmamk_f32 v94, v94, 0x3e38aa3b, v143
	v_fmamk_f32 v95, v95, 0x3e38aa3b, v142
	v_max3_f32 v112, v112, v80, v81
	v_max3_f32 v113, v113, v82, v83
	v_max3_f32 v112, v112, v84, v85
	v_max3_f32 v113, v113, v86, v87
	v_max3_f32 v112, v112, v88, v89
	v_max3_f32 v113, v113, v90, v91
	v_max3_f32 v112, v112, v92, v93
	v_max3_f32 v113, v113, v94, v95
	s_nop 0
	v_max_f32_e32 v113, v113, v113
	v_max_f32_e32 v112, v112, v112
	v_max_f32_e32 v112, v112, v113
	v_mov_b32_e32 v113, v112
	s_nop 1
	v_permlane32_swap_b32_e32 v112, v113
	v_max_f32_e32 v113, v113, v113
	v_max_f32_e32 v112, v112, v112
	v_max_f32_e32 v112, v112, v113
	v_sub_f32_e32 v113, v112, v226
	v_cmp_lt_f32_e32 vcc, s45, v113
	v_max_f32_e32 v112, v226, v112
	s_nop 0
	v_cndmask_b32_e32 v227, v226, v112, vcc
	v_sub_f32 v112, v96, v227
	v_sub_f32 v128, v80, v227
	v_sub_f32 v113, v97, v227
	v_sub_f32 v129, v81, v227
	v_sub_f32 v114, v98, v227
	v_sub_f32 v130, v82, v227
	v_sub_f32 v115, v99, v227
	v_sub_f32 v131, v83, v227
	v_sub_f32 v116, v100, v227
	v_sub_f32 v132, v84, v227
	v_sub_f32 v117, v101, v227
	v_sub_f32 v133, v85, v227
	v_sub_f32 v118, v102, v227
	v_sub_f32 v134, v86, v227
	v_sub_f32 v119, v103, v227
	v_sub_f32 v135, v87, v227
	v_sub_f32 v120, v104, v227
	v_sub_f32 v136, v88, v227
	v_sub_f32 v121, v105, v227
	v_sub_f32 v137, v89, v227
	v_sub_f32 v122, v106, v227
	v_sub_f32 v138, v90, v227
	v_sub_f32 v123, v107, v227
	v_sub_f32 v139, v91, v227
	v_sub_f32 v124, v108, v227
	v_sub_f32 v140, v92, v227
	v_sub_f32 v125, v109, v227
	v_sub_f32 v141, v93, v227
	v_sub_f32 v126, v110, v227
	v_sub_f32 v142, v94, v227
	v_sub_f32 v127, v111, v227
	v_sub_f32 v143, v95, v227
